# GEMM steady K-loops: static s_setprio 1 for the wave in odd hardware wave slot of each SIMD (reset at loop exit), on top of v46
# speedup vs baseline: 1.0026x; 1.0026x over previous
; DEVI f32x4 mfma16(bf16x8 a, bf16x8 b, f32x4 c) { return __builtin_amdgcn_mfma_f32_16x16x32_bf16(a, b, c, 0, 0, 0); }
; template <int MODE, class Epi>
; DEVI void gemm256_phase(int sw, const bf16_t* __restrict__ W, int ldw, const bf16_t* __restrict__ X, int ldx, int K, int nN, char* shm, const Epi& epi) {
;     ...
;         for (int m = 0; m < 8; ++m) At[m] = *(const bf16x8*)(SAp + (2 * m + ks) * 1024 + kx);
; #pragma unroll
;         for (int n = 0; n < 4; ++n) Bf[n] = *(const bf16x8*)(SBp + (2 * n + ks) * 1024 + kx);
; #pragma unroll
;         for (int m = 0; m < 8; ++m)
; #pragma unroll
;           for (int n = 0; n < 4; ++n) acc[m][n] = mfma16(At[m], Bf[n], acc[m][n]);
;         __builtin_amdgcn_sched_barrier(0);
;         if (ks == 0 && wid >= 4) {
;           if (st_own) stage(cur ^ 1, n0, m0, kt0 + t + 1);
;           else if (st_next) stage(cur ^ 1, n1, m1, kt1);
;         }
;       }
;       asm volatile("s_waitcnt vmcnt(0)" ::: "memory");
;       __syncthreads();
.Lmy_xexit_168:
	s_setprio 0
	s_waitcnt lgkmcnt(1)
	v_mfma_f32_16x16x32_bf16 v[28:31], v[244:247], v[134:137], v[28:31]
	v_mfma_f32_16x16x32_bf16 v[24:27], v[244:247], v[138:141], v[24:27]
	v_mfma_f32_16x16x32_bf16 v[20:23], v[244:247], v[142:145], v[20:23]
	v_mfma_f32_16x16x32_bf16 v[16:19], v[244:247], v[146:149], v[16:19]
	s_waitcnt lgkmcnt(0)
	v_mfma_f32_16x16x32_bf16 v[12:15], v[248:251], v[134:137], v[12:15]
	v_mfma_f32_16x16x32_bf16 v[8:11], v[248:251], v[138:141], v[8:11]
	v_mfma_f32_16x16x32_bf16 v[4:7], v[248:251], v[142:145], v[4:7]
	v_mfma_f32_16x16x32_bf16 v[0:3], v[248:251], v[146:149], v[0:3]
	s_waitcnt vmcnt(0)
	s_barrier
	s_branch .LBB0_186
.LBB0_168:
	s_getreg_b32 s98, hwreg(HW_REG_HW_ID, 0, 1)
	s_cmp_eq_u32 s98, 1
	s_cbranch_scc0 .Lmy_np_168
	s_setprio 1

; DEVI f32x4 mfma16(bf16x8 a, bf16x8 b, f32x4 c) { return __builtin_amdgcn_mfma_f32_16x16x32_bf16(a, b, c, 0, 0, 0); }
; template <int MODE, class Epi>
; DEVI void gemm256_phase(int sw, const bf16_t* __restrict__ W, int ldw, const bf16_t* __restrict__ X, int ldx, int K, int nN, char* shm, const Epi& epi) {
;     ...
;         for (int m = 0; m < 8; ++m) At[m] = *(const bf16x8*)(SAp + (2 * m + ks) * 1024 + kx);
; #pragma unroll
;         for (int n = 0; n < 4; ++n) Bf[n] = *(const bf16x8*)(SBp + (2 * n + ks) * 1024 + kx);
; #pragma unroll
;         for (int m = 0; m < 8; ++m)
; #pragma unroll
;           for (int n = 0; n < 4; ++n) acc[m][n] = mfma16(At[m], Bf[n], acc[m][n]);
;         __builtin_amdgcn_sched_barrier(0);
;         if (ks == 0 && wid >= 4) {
;           if (st_own) stage(cur ^ 1, n0, m0, kt0 + t + 1);
;           else if (st_next) stage(cur ^ 1, n1, m1, kt1);
;         }
;       }
;       asm volatile("s_waitcnt vmcnt(0)" ::: "memory");
;       __syncthreads();
.Lmy_xexit_704:
	s_setprio 0
	s_waitcnt lgkmcnt(1)
	v_mfma_f32_16x16x32_bf16 v[28:31], v[244:247], v[134:137], v[28:31]
	v_mfma_f32_16x16x32_bf16 v[24:27], v[244:247], v[142:145], v[24:27]
	v_mfma_f32_16x16x32_bf16 v[20:23], v[244:247], v[146:149], v[20:23]
	v_mfma_f32_16x16x32_bf16 v[16:19], v[244:247], v[150:153], v[16:19]
	s_waitcnt lgkmcnt(0)
	v_mfma_f32_16x16x32_bf16 v[12:15], v[248:251], v[134:137], v[12:15]
	v_mfma_f32_16x16x32_bf16 v[8:11], v[248:251], v[142:145], v[8:11]
	v_mfma_f32_16x16x32_bf16 v[4:7], v[248:251], v[146:149], v[4:7]
	v_mfma_f32_16x16x32_bf16 v[0:3], v[248:251], v[150:153], v[0:3]
	s_waitcnt vmcnt(0)
	s_barrier
	s_branch .LBB0_724
